# attention score-minus-max as packed adds; GLA scan LDS reads batched (on top of pass3 prefetch)
# baseline (speedup 1.0000x reference)
.LBB0_595:
	s_mul_hi_i32 s0, s8, 0x3e0f83e1
	s_lshr_b32 s1, s0, 31
	s_ashr_i32 s0, s0, 5
	s_add_i32 s0, s0, s1
	s_mul_i32 s1, s0, 0x84
	s_sub_i32 s20, s8, s1
	s_and_b32 s19, s0, 1
	s_bfe_u32 s21, s0, 0x20001
	s_lshl_b32 s1, s20, 6
	s_cmp_lt_i32 s20, 4
	s_cselect_b32 s9, s7, s6
	v_mov_b32_e32 v16, v207
	s_add_i32 s9, s9, s1
	v_mov_b32_e32 v10, v207
	s_cmp_eq_u32 s19, 0
	s_barrier
	s_cselect_b64 s[42:43], -1, 0
	v_ashrrev_i32_e32 v4, 3, v10
	v_lshlrev_b32_e32 v0, 4, v10
	s_cmp_eq_u32 s19, 1
	v_and_b32_e32 v2, 0x70, v0
	v_add_u32_e32 v3, s9, v4
	v_mov_b64_e32 v[0:1], s[36:37]
	s_cselect_b64 s[2:3], -1, 0
	s_and_b32 s22, s0, -8
	v_mad_i64_i32 v[0:1], s[0:1], v3, s14, v[0:1]
	s_lshl_b32 s26, s21, 8
	s_lshl_b32 s18, s21, 7
	v_lshl_add_u64 v[0:1], v[0:1], 0, s[26:27]
	v_lshlrev_b32_e32 v128, 1, v2
	v_lshlrev_b32_e32 v3, 9, v4
	v_lshlrev_b32_e32 v5, 2, v2
	v_lshl_add_u64 v[0:1], v[0:1], 0, v[128:129]
	s_mov_b64 s[0:1], -1
	s_movk_i32 s100, 0xe00
	s_cmp_eq_u32 s22, 8
	s_cselect_b32 s100, 0x400, s100
	s_lshl_b32 s101, s21, 7
	s_add_i32 s100, s100, s101
	s_lshl_b32 s100, s100, 1
	s_mov_b32 s101, 0
	v_and_b32_e32 v162, 63, v207
	v_or_b32_e32 v162, s9, v162
	v_mul_u32_u24_e32 v162, 0x1200, v162
	v_mov_b32_e32 v163, 0
	v_lshl_add_u64 v[162:163], v[162:163], 1, s[36:37]
	v_lshl_add_u64 v[162:163], v[162:163], 0, s[100:101]
	v_ashrrev_i32_e32 v164, 2, v207
	v_and_b32_e32 v164, -16, v164
	v_mov_b32_e32 v165, 0
	v_lshl_add_u64 v[162:163], v[164:165], 1, v[162:163]
	global_load_dwordx4 v[154:157], v[162:163], off
	global_load_dwordx4 v[158:161], v[162:163], off offset:16
	s_cmp_lg_u32 s22, 8
	v_add3_u32 v5, 0, v3, v5
	s_cbranch_scc0 .LBB0_613
	s_and_b64 s[0:1], s[42:43], exec
	s_cselect_b32 s26, s15, 0x1800
	v_lshl_add_u64 v[12:13], v[0:1], 0, s[26:27]
	global_load_dwordx4 v[6:9], v[12:13], off
	global_load_dwordx4 v[26:29], v[12:13], off offset:16
	v_or_b32_e32 v2, s18, v2
	v_lshlrev_b32_e32 v128, 2, v2
	v_lshl_add_u64 v[2:3], s[78:79], 0, v[128:129]
	s_waitcnt vmcnt(0) lgkmcnt(0)
	v_lshlrev_b32_e32 v11, 16, v6
	v_and_b32_e32 v25, 0xffff0000, v6
	global_load_dword v6, v[2:3], off
	v_lshlrev_b32_e32 v15, 16, v8
	v_and_b32_e32 v12, 0xffff0000, v8
	v_mul_f32_e32 v8, 0xbfb8aa3b, v11
	v_exp_f32_e32 v8, v8
	v_lshlrev_b32_e32 v20, 16, v9
	v_and_b32_e32 v17, 0xffff0000, v9
	v_lshlrev_b32_e32 v24, 16, v26
	v_add_f32_e32 v8, 1.0, v8
	v_rcp_f32_e32 v11, v8
	v_and_b32_e32 v21, 0xffff0000, v26
	v_lshlrev_b32_e32 v23, 16, v27
	v_and_b32_e32 v22, 0xffff0000, v27
	v_lshlrev_b32_e32 v19, 16, v28
	v_and_b32_e32 v18, 0xffff0000, v28
	v_mul_f32_e32 v8, 1.0, v11
	v_mul_f32_e32 v9, 0xbfb8aa3b, v25
	v_exp_f32_e32 v9, v9
	v_lshlrev_b32_e32 v30, 16, v7
	v_and_b32_e32 v31, 0xffff0000, v7
	v_lshlrev_b32_e32 v14, 16, v29
	v_add_f32_e32 v9, 1.0, v9
	v_rcp_f32_e32 v25, v9
	v_and_b32_e32 v13, 0xffff0000, v29
	v_mul_f32_e32 v15, 0xbfb8aa3b, v15
	v_exp_f32_e32 v15, v15
	v_mul_f32_e32 v9, 1.0, v25
	v_mul_f32_e32 v11, 0xbfb8aa3b, v30
	v_exp_f32_e32 v11, v11
	v_add_f32_e32 v15, 1.0, v15
	v_mul_f32_e32 v12, 0xbfb8aa3b, v12
	v_exp_f32_e32 v12, v12
	v_add_f32_e32 v11, 1.0, v11
	v_mul_f32_e32 v20, 0xbfb8aa3b, v20
	v_exp_f32_e32 v20, v20
	v_add_f32_e32 v12, 1.0, v12
	v_mul_f32_e32 v17, 0xbfb8aa3b, v17
	v_exp_f32_e32 v17, v17
	v_add_f32_e32 v20, 1.0, v20
	v_mul_f32_e32 v24, 0xbfb8aa3b, v24
	v_exp_f32_e32 v24, v24
	v_add_f32_e32 v17, 1.0, v17
	v_mul_f32_e32 v21, 0xbfb8aa3b, v21
	v_exp_f32_e32 v21, v21
	v_add_f32_e32 v24, 1.0, v24
	v_mul_f32_e32 v23, 0xbfb8aa3b, v23
	v_exp_f32_e32 v23, v23
	v_add_f32_e32 v21, 1.0, v21
	v_mul_f32_e32 v22, 0xbfb8aa3b, v22
	v_exp_f32_e32 v22, v22
	v_add_f32_e32 v23, 1.0, v23
	v_mul_f32_e32 v19, 0xbfb8aa3b, v19
	v_exp_f32_e32 v19, v19
	v_add_f32_e32 v22, 1.0, v22
	v_mul_f32_e32 v18, 0xbfb8aa3b, v18
	v_exp_f32_e32 v18, v18
	v_add_f32_e32 v19, 1.0, v19
	v_mul_f32_e32 v14, 0xbfb8aa3b, v14
	s_waitcnt vmcnt(0) lgkmcnt(0)
	v_sub_f32_e32 v7, 1.0, v6
	v_fmac_f32_e32 v6, v7, v8
	v_cmp_gt_f32_e32 vcc, s12, v6
	v_add_f32_e32 v18, 1.0, v18
	v_exp_f32_e32 v14, v14
	v_cndmask_b32_e64 v7, 0, 32, vcc
	v_ldexp_f32 v7, v6, v7
	v_log_f32_e32 v7, v7
	v_add_f32_e32 v14, 1.0, v14
	v_mul_f32_e32 v13, 0xbfb8aa3b, v13
	v_exp_f32_e32 v13, v13
	v_mul_f32_e32 v8, 0x3f317217, v7
	v_fma_f32 v8, v7, s86, -v8
	v_fmac_f32_e32 v8, 0x3377d1cf, v7
	v_fmac_f32_e32 v8, 0x3f317217, v7
	v_cmp_lt_f32_e64 s[0:1], |v7|, s87
	v_add_f32_e32 v13, 1.0, v13
	s_nop 0
	v_cndmask_b32_e64 v7, v7, v8, s[0:1]
	v_cndmask_b32_e32 v8, 0, v231, vcc
	v_sub_f32_e32 v7, v7, v8
	ds_write_b32 v5, v7
	global_load_dword v7, v[2:3], off offset:4
	s_waitcnt vmcnt(0) lgkmcnt(0)
	v_sub_f32_e32 v8, 1.0, v7
	v_fmac_f32_e32 v7, v8, v9
	v_cmp_gt_f32_e32 vcc, s12, v7
	s_nop 1
	v_cndmask_b32_e64 v8, 0, 32, vcc
	v_ldexp_f32 v8, v7, v8
	v_log_f32_e32 v8, v8
	s_nop 0
	v_mul_f32_e32 v9, 0x3f317217, v8
	v_fma_f32 v9, v8, s86, -v9
	v_fmac_f32_e32 v9, 0x3377d1cf, v8
	v_fmac_f32_e32 v9, 0x3f317217, v8
	v_cmp_lt_f32_e64 s[0:1], |v8|, s87
	s_nop 1
	v_cndmask_b32_e64 v8, v8, v9, s[0:1]
	v_cndmask_b32_e32 v9, 0, v231, vcc
	v_sub_f32_e32 v8, v8, v9
	ds_write_b32 v5, v8 offset:4
	global_load_dword v8, v[2:3], off offset:8
	v_rcp_f32_e32 v26, v11
	s_waitcnt vmcnt(0) lgkmcnt(0)
	v_sub_f32_e32 v9, 1.0, v8
	v_mul_f32_e32 v11, 1.0, v26
	v_mul_f32_e32 v25, 0xbfb8aa3b, v31
	v_exp_f32_e32 v25, v25
	v_fmac_f32_e32 v8, v11, v9
	v_add_f32_e32 v25, 1.0, v25
	v_rcp_f32_e32 v27, v25
	s_nop 0
	v_cmp_gt_f32_e32 vcc, s12, v8
	v_mul_f32_e32 v25, 1.0, v27
	s_nop 0
	v_cndmask_b32_e64 v9, 0, 32, vcc
	v_ldexp_f32 v9, v8, v9
	v_log_f32_e32 v9, v9
	s_nop 0
	v_mul_f32_e32 v11, 0x3f317217, v9
	v_fma_f32 v11, v9, s86, -v11
	v_fmac_f32_e32 v11, 0x3377d1cf, v9
	v_fmac_f32_e32 v11, 0x3f317217, v9
	v_cmp_lt_f32_e64 s[0:1], |v9|, s87
	s_nop 1
	v_cndmask_b32_e64 v9, v9, v11, s[0:1]
	v_cndmask_b32_e32 v11, 0, v231, vcc
	v_sub_f32_e32 v9, v9, v11
	ds_write_b32 v5, v9 offset:8
	global_load_dword v9, v[2:3], off offset:12
	s_waitcnt vmcnt(0) lgkmcnt(0)
	v_sub_f32_e32 v11, 1.0, v9
	v_fmac_f32_e32 v9, v25, v11
	v_cmp_gt_f32_e32 vcc, s12, v9
	s_nop 1
	v_cndmask_b32_e64 v11, 0, 32, vcc
	v_ldexp_f32 v11, v9, v11
	v_log_f32_e32 v11, v11
	s_nop 0
	v_mul_f32_e32 v25, 0x3f317217, v11
	v_fma_f32 v25, v11, s86, -v25
	v_fmac_f32_e32 v25, 0x3377d1cf, v11
	v_fmac_f32_e32 v25, 0x3f317217, v11
	v_cmp_lt_f32_e64 s[0:1], |v11|, s87
	s_nop 1
	v_cndmask_b32_e64 v11, v11, v25, s[0:1]
	v_cndmask_b32_e32 v25, 0, v231, vcc
	v_sub_f32_e32 v11, v11, v25
	ds_write_b32 v5, v11 offset:12
	global_load_dword v11, v[2:3], off offset:16
	v_rcp_f32_e32 v27, v15
	s_waitcnt vmcnt(0) lgkmcnt(0)
	v_sub_f32_e32 v25, 1.0, v11
	v_mul_f32_e32 v15, 1.0, v27
	v_rcp_f32_e32 v27, v12
	v_fmac_f32_e32 v11, v15, v25
	v_cmp_gt_f32_e32 vcc, s12, v11
	v_mul_f32_e32 v26, 1.0, v27
	s_nop 0
	v_cndmask_b32_e64 v12, 0, 32, vcc
	v_ldexp_f32 v12, v11, v12
	v_log_f32_e32 v12, v12
	s_nop 0
	v_mul_f32_e32 v15, 0x3f317217, v12
	v_fma_f32 v15, v12, s86, -v15
	v_fmac_f32_e32 v15, 0x3377d1cf, v12
	v_fmac_f32_e32 v15, 0x3f317217, v12
	v_cmp_lt_f32_e64 s[0:1], |v12|, s87
	s_nop 1
	v_cndmask_b32_e64 v12, v12, v15, s[0:1]
	v_cndmask_b32_e32 v15, 0, v231, vcc
	v_sub_f32_e32 v12, v12, v15
	ds_write_b32 v5, v12 offset:16
	global_load_dword v12, v[2:3], off offset:20
	s_waitcnt vmcnt(0) lgkmcnt(0)
	v_sub_f32_e32 v15, 1.0, v12
	v_fmac_f32_e32 v12, v26, v15
	v_cmp_gt_f32_e32 vcc, s12, v12
	s_nop 1
	v_cndmask_b32_e64 v15, 0, 32, vcc
	v_ldexp_f32 v15, v12, v15
	v_log_f32_e32 v15, v15
	s_nop 0
	v_mul_f32_e32 v25, 0x3f317217, v15
	v_fma_f32 v25, v15, s86, -v25
	v_fmac_f32_e32 v25, 0x3377d1cf, v15
	v_fmac_f32_e32 v25, 0x3f317217, v15
	v_cmp_lt_f32_e64 s[0:1], |v15|, s87
	s_nop 1
	v_cndmask_b32_e64 v15, v15, v25, s[0:1]
	v_cndmask_b32_e32 v25, 0, v231, vcc
	v_sub_f32_e32 v15, v15, v25
	ds_write_b32 v5, v15 offset:20
	global_load_dword v15, v[2:3], off offset:24
	v_rcp_f32_e32 v27, v20
	s_waitcnt vmcnt(0) lgkmcnt(0)
	v_sub_f32_e32 v25, 1.0, v15
	v_mul_f32_e32 v20, 1.0, v27
	v_rcp_f32_e32 v27, v17
	v_fmac_f32_e32 v15, v20, v25
	v_cmp_gt_f32_e32 vcc, s12, v15
	v_mul_f32_e32 v26, 1.0, v27
	s_nop 0
	v_cndmask_b32_e64 v17, 0, 32, vcc
	v_ldexp_f32 v17, v15, v17
	v_log_f32_e32 v17, v17
	s_nop 0
	v_mul_f32_e32 v20, 0x3f317217, v17
	v_fma_f32 v20, v17, s86, -v20
	v_fmac_f32_e32 v20, 0x3377d1cf, v17
	v_fmac_f32_e32 v20, 0x3f317217, v17
	v_cmp_lt_f32_e64 s[0:1], |v17|, s87
	s_nop 1
	v_cndmask_b32_e64 v17, v17, v20, s[0:1]
	v_cndmask_b32_e32 v20, 0, v231, vcc
	v_sub_f32_e32 v17, v17, v20
	ds_write_b32 v5, v17 offset:24
	global_load_dword v17, v[2:3], off offset:28
	s_waitcnt vmcnt(0) lgkmcnt(0)
	v_sub_f32_e32 v20, 1.0, v17
	v_fmac_f32_e32 v17, v26, v20
	v_cmp_gt_f32_e32 vcc, s12, v17
	s_nop 1
	v_cndmask_b32_e64 v20, 0, 32, vcc
	v_ldexp_f32 v20, v17, v20
	v_log_f32_e32 v20, v20
	s_nop 0
	v_mul_f32_e32 v25, 0x3f317217, v20
	v_fma_f32 v25, v20, s86, -v25
	v_fmac_f32_e32 v25, 0x3377d1cf, v20
	v_fmac_f32_e32 v25, 0x3f317217, v20
	v_cmp_lt_f32_e64 s[0:1], |v20|, s87
	s_nop 1
	v_cndmask_b32_e64 v20, v20, v25, s[0:1]
	v_cndmask_b32_e32 v25, 0, v231, vcc
	v_sub_f32_e32 v20, v20, v25
	ds_write_b32 v5, v20 offset:28
	global_load_dword v20, v[2:3], off offset:32
	v_rcp_f32_e32 v27, v24
	s_waitcnt vmcnt(0) lgkmcnt(0)
	v_sub_f32_e32 v25, 1.0, v20
	v_mul_f32_e32 v24, 1.0, v27
	v_rcp_f32_e32 v27, v21
	v_fmac_f32_e32 v20, v24, v25
	v_cmp_gt_f32_e32 vcc, s12, v20
	v_mul_f32_e32 v26, 1.0, v27
	s_nop 0
	v_cndmask_b32_e64 v21, 0, 32, vcc
	v_ldexp_f32 v21, v20, v21
	v_log_f32_e32 v21, v21
	s_nop 0
	v_mul_f32_e32 v24, 0x3f317217, v21
	v_fma_f32 v24, v21, s86, -v24
	v_fmac_f32_e32 v24, 0x3377d1cf, v21
	v_fmac_f32_e32 v24, 0x3f317217, v21
	v_cmp_lt_f32_e64 s[0:1], |v21|, s87
	s_nop 1
	v_cndmask_b32_e64 v21, v21, v24, s[0:1]
	v_cndmask_b32_e32 v24, 0, v231, vcc
	v_sub_f32_e32 v21, v21, v24
	ds_write_b32 v5, v21 offset:32
	global_load_dword v21, v[2:3], off offset:36
	s_waitcnt vmcnt(0) lgkmcnt(0)
	v_sub_f32_e32 v24, 1.0, v21
	v_fmac_f32_e32 v21, v26, v24
	v_cmp_gt_f32_e32 vcc, s12, v21
	s_nop 1
	v_cndmask_b32_e64 v24, 0, 32, vcc
	v_ldexp_f32 v24, v21, v24
	v_log_f32_e32 v24, v24
	s_nop 0
	v_mul_f32_e32 v25, 0x3f317217, v24
	v_fma_f32 v25, v24, s86, -v25
	v_fmac_f32_e32 v25, 0x3377d1cf, v24
	v_fmac_f32_e32 v25, 0x3f317217, v24
	v_cmp_lt_f32_e64 s[0:1], |v24|, s87
	s_nop 1
	v_cndmask_b32_e64 v24, v24, v25, s[0:1]
	v_cndmask_b32_e32 v25, 0, v231, vcc
	v_sub_f32_e32 v24, v24, v25
	ds_write_b32 v5, v24 offset:36
	global_load_dword v24, v[2:3], off offset:40
	v_rcp_f32_e32 v27, v23
	s_waitcnt vmcnt(0) lgkmcnt(0)
	v_sub_f32_e32 v25, 1.0, v24
	v_mul_f32_e32 v23, 1.0, v27
	v_rcp_f32_e32 v27, v22
	v_fmac_f32_e32 v24, v23, v25
	v_cmp_gt_f32_e32 vcc, s12, v24
	v_mul_f32_e32 v26, 1.0, v27
	s_nop 0
	v_cndmask_b32_e64 v22, 0, 32, vcc
	v_ldexp_f32 v22, v24, v22
	v_log_f32_e32 v22, v22
	s_nop 0
	v_mul_f32_e32 v23, 0x3f317217, v22
	v_fma_f32 v23, v22, s86, -v23
	v_fmac_f32_e32 v23, 0x3377d1cf, v22
	v_fmac_f32_e32 v23, 0x3f317217, v22
	v_cmp_lt_f32_e64 s[0:1], |v22|, s87
	s_nop 1
	v_cndmask_b32_e64 v22, v22, v23, s[0:1]
	v_cndmask_b32_e32 v23, 0, v231, vcc
	v_sub_f32_e32 v22, v22, v23
	ds_write_b32 v5, v22 offset:40
	global_load_dword v22, v[2:3], off offset:44
	s_waitcnt vmcnt(0) lgkmcnt(0)
	v_sub_f32_e32 v23, 1.0, v22
	v_fmac_f32_e32 v22, v26, v23
	v_cmp_gt_f32_e32 vcc, s12, v22
	s_nop 1
	v_cndmask_b32_e64 v23, 0, 32, vcc
	v_ldexp_f32 v23, v22, v23
	v_log_f32_e32 v23, v23
	s_nop 0
	v_mul_f32_e32 v25, 0x3f317217, v23
	v_fma_f32 v25, v23, s86, -v25
	v_fmac_f32_e32 v25, 0x3377d1cf, v23
	v_fmac_f32_e32 v25, 0x3f317217, v23
	v_cmp_lt_f32_e64 s[0:1], |v23|, s87
	s_nop 1
	v_cndmask_b32_e64 v23, v23, v25, s[0:1]
	v_cndmask_b32_e32 v25, 0, v231, vcc
	v_sub_f32_e32 v23, v23, v25
	ds_write_b32 v5, v23 offset:44
	global_load_dword v23, v[2:3], off offset:48
	v_rcp_f32_e32 v27, v19
	s_waitcnt vmcnt(0) lgkmcnt(0)
	v_sub_f32_e32 v25, 1.0, v23
	v_mul_f32_e32 v19, 1.0, v27
	v_rcp_f32_e32 v27, v18
	v_fmac_f32_e32 v23, v19, v25
	v_cmp_gt_f32_e32 vcc, s12, v23
	v_mul_f32_e32 v26, 1.0, v27
	s_nop 0
	v_cndmask_b32_e64 v18, 0, 32, vcc
	v_ldexp_f32 v18, v23, v18
	v_log_f32_e32 v18, v18
	s_nop 0
	v_mul_f32_e32 v19, 0x3f317217, v18
	v_fma_f32 v19, v18, s86, -v19
	v_fmac_f32_e32 v19, 0x3377d1cf, v18
	v_fmac_f32_e32 v19, 0x3f317217, v18
	v_cmp_lt_f32_e64 s[0:1], |v18|, s87
	s_nop 1
	v_cndmask_b32_e64 v18, v18, v19, s[0:1]
	v_cndmask_b32_e32 v19, 0, v231, vcc
	v_sub_f32_e32 v18, v18, v19
	ds_write_b32 v5, v18 offset:48
	global_load_dword v18, v[2:3], off offset:52
	s_waitcnt vmcnt(0) lgkmcnt(0)
	v_sub_f32_e32 v19, 1.0, v18
	v_fmac_f32_e32 v18, v26, v19
	v_cmp_gt_f32_e32 vcc, s12, v18
	s_nop 1
	v_cndmask_b32_e64 v19, 0, 32, vcc
	v_ldexp_f32 v19, v18, v19
	v_log_f32_e32 v19, v19
	s_nop 0
	v_mul_f32_e32 v25, 0x3f317217, v19
	v_fma_f32 v25, v19, s86, -v25
	v_fmac_f32_e32 v25, 0x3377d1cf, v19
	v_fmac_f32_e32 v25, 0x3f317217, v19
	v_cmp_lt_f32_e64 s[0:1], |v19|, s87
	s_nop 1
	v_cndmask_b32_e64 v19, v19, v25, s[0:1]
	v_cndmask_b32_e32 v25, 0, v231, vcc
	v_sub_f32_e32 v19, v19, v25
	ds_write_b32 v5, v19 offset:52
	global_load_dword v25, v[2:3], off offset:56
	v_rcp_f32_e32 v27, v14
	s_waitcnt vmcnt(0) lgkmcnt(0)
	v_sub_f32_e32 v19, 1.0, v25
	v_mul_f32_e32 v14, 1.0, v27
	v_rcp_f32_e32 v27, v13
	v_fmac_f32_e32 v25, v14, v19
	v_cmp_gt_f32_e32 vcc, s12, v25
	v_mul_f32_e32 v13, 1.0, v27
	s_nop 0
	v_cndmask_b32_e64 v14, 0, 32, vcc
	v_ldexp_f32 v14, v25, v14
	v_log_f32_e32 v14, v14
	s_nop 0
	v_mul_f32_e32 v19, 0x3f317217, v14
	v_fma_f32 v19, v14, s86, -v19
	v_fmac_f32_e32 v19, 0x3377d1cf, v14
	v_fmac_f32_e32 v19, 0x3f317217, v14
	v_cmp_lt_f32_e64 s[0:1], |v14|, s87
	s_nop 1
	v_cndmask_b32_e64 v14, v14, v19, s[0:1]
	v_cndmask_b32_e32 v19, 0, v231, vcc
	v_sub_f32_e32 v14, v14, v19
	ds_write_b32 v5, v14 offset:56
	global_load_dword v3, v[2:3], off offset:60
	s_waitcnt vmcnt(0) lgkmcnt(0)
	v_sub_f32_e32 v2, 1.0, v3
	v_fmac_f32_e32 v3, v13, v2
	v_cmp_gt_f32_e32 vcc, s12, v3
	s_nop 1
	v_cndmask_b32_e64 v2, 0, 32, vcc
	v_ldexp_f32 v2, v3, v2
	v_log_f32_e32 v2, v2
	s_nop 0
	v_mul_f32_e32 v13, 0x3f317217, v2
	v_fma_f32 v13, v2, s86, -v13
	v_fmac_f32_e32 v13, 0x3377d1cf, v2
	v_fmac_f32_e32 v13, 0x3f317217, v2
	v_cmp_lt_f32_e64 s[0:1], |v2|, s87
	s_nop 1
	v_cndmask_b32_e64 v2, v2, v13, s[0:1]
	v_cndmask_b32_e32 v13, 0, v231, vcc
	v_sub_f32_e32 v2, v2, v13
	v_ashrrev_i32_e32 v13, 7, v10
	v_and_b32_e32 v10, 0x7f, v10
	v_lshlrev_b32_e32 v14, 13, v13
	v_lshlrev_b32_e32 v19, 2, v10
	ds_write_b32 v5, v2 offset:60
	v_add3_u32 v2, 0, v19, v14
	s_mov_b64 s[0:1], -1
	s_and_b64 vcc, exec, s[2:3]
	s_waitcnt lgkmcnt(0)
	s_barrier
	s_cbranch_vccz .LBB0_598
	ds_read2st64_b32 v[164:165], v2 offset0:28 offset1:30
	ds_read2st64_b32 v[166:167], v2 offset0:24 offset1:26
	ds_read2st64_b32 v[168:169], v2 offset0:20 offset1:22
	ds_read2st64_b32 v[170:171], v2 offset0:16 offset1:18
	ds_read2st64_b32 v[172:173], v2 offset0:12 offset1:14
	ds_read2st64_b32 v[174:175], v2 offset0:8 offset1:10
	ds_read2st64_b32 v[176:177], v2 offset0:4 offset1:6
	ds_read2st64_b32 v[178:179], v2 offset1:2
	s_mov_b64 s[0:1], 0
	s_waitcnt lgkmcnt(0)
	v_add_f32_e32 v27, 0, v165
	v_add_f32_e32 v28, v27, v164
	ds_write2st64_b32 v2, v28, v27 offset0:28 offset1:30
	v_add_f32_e32 v27, v28, v167
	v_add_f32_e32 v28, v27, v166
	ds_write2st64_b32 v2, v28, v27 offset0:24 offset1:26
	v_add_f32_e32 v27, v28, v169
	v_add_f32_e32 v28, v27, v168
	ds_write2st64_b32 v2, v28, v27 offset0:20 offset1:22
	v_add_f32_e32 v27, v28, v171
	v_add_f32_e32 v28, v27, v170
	ds_write2st64_b32 v2, v28, v27 offset0:16 offset1:18
	v_add_f32_e32 v27, v28, v173
	v_add_f32_e32 v28, v27, v172
	ds_write2st64_b32 v2, v28, v27 offset0:12 offset1:14
	v_add_f32_e32 v27, v28, v175
	v_add_f32_e32 v28, v27, v174
	ds_write2st64_b32 v2, v28, v27 offset0:8 offset1:10
	v_add_f32_e32 v27, v28, v177
	v_add_f32_e32 v28, v27, v176
	ds_write2st64_b32 v2, v28, v27 offset0:4 offset1:6
	v_add_f32_e32 v27, v28, v179
	v_add_f32_e32 v26, v27, v178
	ds_write2st64_b32 v2, v26, v27 offset1:2
.LBB0_598:
	s_andn2_b64 vcc, exec, s[0:1]
	s_cbranch_vccnz .LBB0_600
	ds_read2st64_b32 v[164:165], v2 offset1:2
	ds_read2st64_b32 v[166:167], v2 offset0:4 offset1:6
	ds_read2st64_b32 v[168:169], v2 offset0:8 offset1:10
	ds_read2st64_b32 v[170:171], v2 offset0:12 offset1:14
	ds_read2st64_b32 v[172:173], v2 offset0:16 offset1:18
	ds_read2st64_b32 v[174:175], v2 offset0:20 offset1:22
	ds_read2st64_b32 v[176:177], v2 offset0:24 offset1:26
	ds_read2st64_b32 v[178:179], v2 offset0:28 offset1:30
	s_waitcnt lgkmcnt(0)
	v_add_f32_e32 v26, 0, v164
	v_add_f32_e32 v28, v26, v165
	ds_write2st64_b32 v2, v26, v28 offset1:2
	v_add_f32_e32 v26, v28, v166
	v_add_f32_e32 v28, v26, v167
	ds_write2st64_b32 v2, v26, v28 offset0:4 offset1:6
	v_add_f32_e32 v26, v28, v168
	v_add_f32_e32 v28, v26, v169
	ds_write2st64_b32 v2, v26, v28 offset0:8 offset1:10
	v_add_f32_e32 v26, v28, v170
	v_add_f32_e32 v28, v26, v171
	ds_write2st64_b32 v2, v26, v28 offset0:12 offset1:14
	v_add_f32_e32 v26, v28, v172
	v_add_f32_e32 v28, v26, v173
	ds_write2st64_b32 v2, v26, v28 offset0:16 offset1:18
	v_add_f32_e32 v26, v28, v174
	v_add_f32_e32 v28, v26, v175
	ds_write2st64_b32 v2, v26, v28 offset0:20 offset1:22
	v_add_f32_e32 v26, v28, v176
	v_add_f32_e32 v28, v26, v177
	ds_write2st64_b32 v2, v26, v28 offset0:24 offset1:26
	v_add_f32_e32 v26, v28, v178
	v_add_f32_e32 v27, v26, v179
	ds_write2st64_b32 v2, v26, v27 offset0:28 offset1:30

.LBB0_612:
	v_sub_f32_e32 v35, 1.0, v6
	v_sub_f32_e32 v34, 1.0, v7
	s_barrier
	ds_read2st64_b32 v[164:165], v2 offset1:2
	ds_read2st64_b32 v[166:167], v2 offset0:4 offset1:6
	ds_read2st64_b32 v[168:169], v2 offset0:8 offset1:10
	ds_read2st64_b32 v[170:171], v2 offset0:12 offset1:14
	ds_read2st64_b32 v[172:173], v2 offset0:16 offset1:18
	ds_read2st64_b32 v[174:175], v2 offset0:20 offset1:22
	ds_read2st64_b32 v[176:177], v2 offset0:24 offset1:26
	ds_read2st64_b32 v[178:179], v2 offset0:28 offset1:30
	v_sub_f32_e32 v28, 1.0, v17
	v_sub_f32_e32 v17, 1.0, v3
	v_sub_f32_e32 v33, 1.0, v8
	v_sub_f32_e32 v32, 1.0, v9
	s_waitcnt lgkmcnt(0)
	v_add_f32_e32 v3, v36, v164
	v_add_f32_e32 v6, v36, v165
	ds_write2st64_b32 v2, v3, v6 offset1:2
	v_sub_f32_e32 v31, 1.0, v11
	v_sub_f32_e32 v30, 1.0, v12
	v_sub_f32_e32 v29, 1.0, v15
	v_sub_f32_e32 v27, 1.0, v20
	v_add_f32_e32 v3, v36, v166
	v_add_f32_e32 v6, v36, v167
	ds_write2st64_b32 v2, v3, v6 offset0:4 offset1:6
	v_sub_f32_e32 v26, 1.0, v21
	v_sub_f32_e32 v24, 1.0, v24
	v_sub_f32_e32 v21, 1.0, v22
	v_sub_f32_e32 v20, 1.0, v23
	v_add_f32_e32 v3, v36, v168
	v_add_f32_e32 v6, v36, v169
	ds_write2st64_b32 v2, v3, v6 offset0:8 offset1:10
	v_sub_f32_e32 v19, 1.0, v18
	v_sub_f32_e32 v18, 1.0, v25
	s_mov_b64 s[0:1], 0
	v_add_f32_e32 v3, v36, v170
	v_add_f32_e32 v6, v36, v171
	ds_write2st64_b32 v2, v3, v6 offset0:12 offset1:14
	v_add_f32_e32 v3, v36, v172
	v_add_f32_e32 v6, v36, v173
	ds_write2st64_b32 v2, v3, v6 offset0:16 offset1:18
	v_add_f32_e32 v3, v36, v174
	v_add_f32_e32 v6, v36, v175
	ds_write2st64_b32 v2, v3, v6 offset0:20 offset1:22
	v_add_f32_e32 v3, v36, v176
	v_add_f32_e32 v6, v36, v177
	ds_write2st64_b32 v2, v3, v6 offset0:24 offset1:26
	v_add_f32_e32 v3, v36, v178
	v_add_f32_e32 v6, v36, v179
	ds_write2st64_b32 v2, v3, v6 offset0:28 offset1:30
	s_waitcnt lgkmcnt(0)
	s_barrier

.Lp3_xdone:
	s_waitcnt vmcnt(0) lgkmcnt(0)
	v_lshlrev_b32_e32 v20, 16, v16
	v_and_b32_e32 v112, 0xffff0000, v16
	v_or_b32_e32 v16, s20, v111
	v_lshlrev_b32_e32 v128, 2, v16
	v_lshlrev_b32_e32 v115, 16, v17
	v_and_b32_e32 v120, 0xffff0000, v17
	v_lshl_add_u64 v[16:17], s[78:79], 0, v[128:129]
	global_load_dword v111, v[16:17], off
	v_lshlrev_b32_e32 v31, 16, v19
	v_and_b32_e32 v30, 0xffff0000, v19
	v_mul_f32_e32 v19, 0xbfb8aa3b, v20
	v_exp_f32_e32 v19, v19
	v_lshlrev_b32_e32 v29, 16, v116
	v_and_b32_e32 v28, 0xffff0000, v116
	v_lshlrev_b32_e32 v27, 16, v117
	v_add_f32_e32 v19, 1.0, v19
	v_rcp_f32_e32 v116, v19
	v_and_b32_e32 v26, 0xffff0000, v117
	v_lshlrev_b32_e32 v25, 16, v118
	v_and_b32_e32 v24, 0xffff0000, v118
	v_lshlrev_b32_e32 v23, 16, v119
	v_and_b32_e32 v22, 0xffff0000, v119
	v_mul_f32_e32 v19, 1.0, v116
	v_mul_f32_e32 v20, 0xbfb8aa3b, v112
	v_exp_f32_e32 v20, v20
	v_lshlrev_b32_e32 v114, 16, v18
	v_and_b32_e32 v21, 0xffff0000, v18
	v_mul_f32_e32 v114, 0xbfb8aa3b, v114
	v_add_f32_e32 v20, 1.0, v20
	v_rcp_f32_e32 v116, v20
	v_exp_f32_e32 v114, v114
	v_mul_f32_e32 v21, 0xbfb8aa3b, v21
	v_exp_f32_e32 v21, v21
	v_mul_f32_e32 v20, 1.0, v116
	v_add_f32_e32 v114, 1.0, v114
	v_add_f32_e32 v21, 1.0, v21
	v_mul_f32_e32 v31, 0xbfb8aa3b, v31
	v_exp_f32_e32 v31, v31
	v_mul_f32_e32 v30, 0xbfb8aa3b, v30
	v_exp_f32_e32 v30, v30
	v_mul_f32_e32 v29, 0xbfb8aa3b, v29
	v_add_f32_e32 v31, 1.0, v31
	v_exp_f32_e32 v29, v29
	v_add_f32_e32 v30, 1.0, v30
	v_mul_f32_e32 v28, 0xbfb8aa3b, v28
	v_exp_f32_e32 v28, v28
	v_add_f32_e32 v29, 1.0, v29
	v_mul_f32_e32 v27, 0xbfb8aa3b, v27
	v_exp_f32_e32 v27, v27
	v_add_f32_e32 v28, 1.0, v28
	v_mul_f32_e32 v26, 0xbfb8aa3b, v26
	v_exp_f32_e32 v26, v26
	v_add_f32_e32 v27, 1.0, v27
	v_mul_f32_e32 v25, 0xbfb8aa3b, v25
	v_exp_f32_e32 v25, v25
	v_add_f32_e32 v26, 1.0, v26
	v_mul_f32_e32 v24, 0xbfb8aa3b, v24
	v_exp_f32_e32 v24, v24
	v_add_f32_e32 v25, 1.0, v25
	v_mul_f32_e32 v23, 0xbfb8aa3b, v23
	v_exp_f32_e32 v23, v23
	v_add_f32_e32 v24, 1.0, v24
	v_mul_f32_e32 v22, 0xbfb8aa3b, v22
	v_exp_f32_e32 v22, v22
	v_add_f32_e32 v23, 1.0, v23
	s_waitcnt vmcnt(0) lgkmcnt(0)
	v_sub_f32_e32 v18, 1.0, v111
	v_fmac_f32_e32 v111, v18, v19
	v_cmp_gt_f32_e32 vcc, s12, v111
	v_add_f32_e32 v22, 1.0, v22
	s_nop 0
	v_cndmask_b32_e64 v18, 0, 32, vcc
	v_ldexp_f32 v18, v111, v18
	v_log_f32_e32 v18, v18
	s_nop 0
	v_mul_f32_e32 v19, 0x3f317217, v18
	v_fma_f32 v19, v18, s86, -v19
	v_fmac_f32_e32 v19, 0x3377d1cf, v18
	v_fmac_f32_e32 v19, 0x3f317217, v18
	v_cmp_lt_f32_e64 s[0:1], |v18|, s87
	s_nop 1
	v_cndmask_b32_e64 v18, v18, v19, s[0:1]
	v_cndmask_b32_e32 v19, 0, v231, vcc
	v_sub_f32_e32 v18, v18, v19
	ds_write_b32 v109, v18
	global_load_dword v112, v[16:17], off offset:4
	s_waitcnt vmcnt(0) lgkmcnt(0)
	v_sub_f32_e32 v18, 1.0, v112
	v_fmac_f32_e32 v112, v18, v20
	v_cmp_gt_f32_e32 vcc, s12, v112
	v_mul_f32_e32 v20, 0xbfb8aa3b, v115
	v_exp_f32_e32 v20, v20
	v_cndmask_b32_e64 v18, 0, 32, vcc
	v_ldexp_f32 v18, v112, v18
	v_log_f32_e32 v18, v18
	v_add_f32_e32 v20, 1.0, v20
	v_mul_f32_e32 v19, 0x3f317217, v18
	v_fma_f32 v19, v18, s86, -v19
	v_fmac_f32_e32 v19, 0x3377d1cf, v18
	v_fmac_f32_e32 v19, 0x3f317217, v18
	v_cmp_lt_f32_e64 s[0:1], |v18|, s87
	s_nop 1
	v_cndmask_b32_e64 v18, v18, v19, s[0:1]
	v_cndmask_b32_e32 v19, 0, v231, vcc
	v_sub_f32_e32 v18, v18, v19
	ds_write_b32 v109, v18 offset:4
	global_load_dword v18, v[16:17], off offset:8
	v_rcp_f32_e32 v116, v20
	s_waitcnt vmcnt(0) lgkmcnt(0)
	v_sub_f32_e32 v19, 1.0, v18
	v_mul_f32_e32 v20, 1.0, v116
	v_mul_f32_e32 v115, 0xbfb8aa3b, v120
	v_exp_f32_e32 v115, v115
	v_fmac_f32_e32 v18, v20, v19
	v_add_f32_e32 v115, 1.0, v115
	v_rcp_f32_e32 v117, v115
	s_nop 0
	v_cmp_gt_f32_e32 vcc, s12, v18
	v_mul_f32_e32 v115, 1.0, v117
	s_nop 0
	v_cndmask_b32_e64 v19, 0, 32, vcc
	v_ldexp_f32 v19, v18, v19
	v_log_f32_e32 v19, v19
	s_nop 0
	v_mul_f32_e32 v20, 0x3f317217, v19
	v_fma_f32 v20, v19, s86, -v20
	v_fmac_f32_e32 v20, 0x3377d1cf, v19
	v_fmac_f32_e32 v20, 0x3f317217, v19
	v_cmp_lt_f32_e64 s[0:1], |v19|, s87
	s_nop 1
	v_cndmask_b32_e64 v19, v19, v20, s[0:1]
	v_cndmask_b32_e32 v20, 0, v231, vcc
	v_sub_f32_e32 v19, v19, v20
	ds_write_b32 v109, v19 offset:8
	global_load_dword v19, v[16:17], off offset:12
	s_waitcnt vmcnt(0) lgkmcnt(0)
	v_sub_f32_e32 v20, 1.0, v19
	v_fmac_f32_e32 v19, v115, v20
	v_cmp_gt_f32_e32 vcc, s12, v19
	s_nop 1
	v_cndmask_b32_e64 v20, 0, 32, vcc
	v_ldexp_f32 v20, v19, v20
	v_log_f32_e32 v20, v20
	s_nop 0
	v_mul_f32_e32 v115, 0x3f317217, v20
	v_fma_f32 v115, v20, s86, -v115
	v_fmac_f32_e32 v115, 0x3377d1cf, v20
	v_fmac_f32_e32 v115, 0x3f317217, v20
	v_cmp_lt_f32_e64 s[0:1], |v20|, s87
	s_nop 1
	v_cndmask_b32_e64 v20, v20, v115, s[0:1]
	v_cndmask_b32_e32 v115, 0, v231, vcc
	v_sub_f32_e32 v20, v20, v115
	ds_write_b32 v109, v20 offset:12
	global_load_dword v20, v[16:17], off offset:16
	v_rcp_f32_e32 v117, v114
	s_waitcnt vmcnt(0) lgkmcnt(0)
	v_sub_f32_e32 v115, 1.0, v20
	v_mul_f32_e32 v114, 1.0, v117
	v_rcp_f32_e32 v117, v21
	v_fmac_f32_e32 v20, v114, v115
	v_cmp_gt_f32_e32 vcc, s12, v20
	v_mul_f32_e32 v116, 1.0, v117
	s_nop 0
	v_cndmask_b32_e64 v21, 0, 32, vcc
	v_ldexp_f32 v21, v20, v21
	v_log_f32_e32 v21, v21
	s_nop 0
	v_mul_f32_e32 v114, 0x3f317217, v21
	v_fma_f32 v114, v21, s86, -v114
	v_fmac_f32_e32 v114, 0x3377d1cf, v21
	v_fmac_f32_e32 v114, 0x3f317217, v21
	v_cmp_lt_f32_e64 s[0:1], |v21|, s87
	s_nop 1
	v_cndmask_b32_e64 v21, v21, v114, s[0:1]
	v_cndmask_b32_e32 v114, 0, v231, vcc
	v_sub_f32_e32 v21, v21, v114
	ds_write_b32 v109, v21 offset:16
	global_load_dword v21, v[16:17], off offset:20
	s_waitcnt vmcnt(0) lgkmcnt(0)
	v_sub_f32_e32 v114, 1.0, v21
	v_fmac_f32_e32 v21, v116, v114
	v_cmp_gt_f32_e32 vcc, s12, v21
	s_nop 1
	v_cndmask_b32_e64 v114, 0, 32, vcc
	v_ldexp_f32 v114, v21, v114
	v_log_f32_e32 v114, v114
	s_nop 0
	v_mul_f32_e32 v115, 0x3f317217, v114
	v_fma_f32 v115, v114, s86, -v115
	v_fmac_f32_e32 v115, 0x3377d1cf, v114
	v_fmac_f32_e32 v115, 0x3f317217, v114
	v_cmp_lt_f32_e64 s[0:1], |v114|, s87
	s_nop 1
	v_cndmask_b32_e64 v114, v114, v115, s[0:1]
	v_cndmask_b32_e32 v115, 0, v231, vcc
	v_sub_f32_e32 v114, v114, v115
	ds_write_b32 v109, v114 offset:20
	global_load_dword v114, v[16:17], off offset:24
	v_rcp_f32_e32 v117, v31
	s_waitcnt vmcnt(0) lgkmcnt(0)
	v_sub_f32_e32 v115, 1.0, v114
	v_mul_f32_e32 v31, 1.0, v117
	v_rcp_f32_e32 v117, v30
	v_fmac_f32_e32 v114, v31, v115
	v_cmp_gt_f32_e32 vcc, s12, v114
	v_mul_f32_e32 v30, 1.0, v117
	s_nop 0
	v_cndmask_b32_e64 v31, 0, 32, vcc
	v_ldexp_f32 v31, v114, v31
	v_log_f32_e32 v31, v31
	s_nop 0
	v_mul_f32_e32 v115, 0x3f317217, v31
	v_fma_f32 v115, v31, s86, -v115
	v_fmac_f32_e32 v115, 0x3377d1cf, v31
	v_fmac_f32_e32 v115, 0x3f317217, v31
	v_cmp_lt_f32_e64 s[0:1], |v31|, s87
	s_nop 1
	v_cndmask_b32_e64 v31, v31, v115, s[0:1]
	v_cndmask_b32_e32 v115, 0, v231, vcc
	v_sub_f32_e32 v31, v31, v115
	ds_write_b32 v109, v31 offset:24
	global_load_dword v115, v[16:17], off offset:28
	s_waitcnt vmcnt(0) lgkmcnt(0)
	v_sub_f32_e32 v31, 1.0, v115
	v_fmac_f32_e32 v115, v30, v31
	v_cmp_gt_f32_e32 vcc, s12, v115
	s_nop 1
	v_cndmask_b32_e64 v30, 0, 32, vcc
	v_ldexp_f32 v30, v115, v30
	v_log_f32_e32 v30, v30
	s_nop 0
	v_mul_f32_e32 v31, 0x3f317217, v30
	v_fma_f32 v31, v30, s86, -v31
	v_fmac_f32_e32 v31, 0x3377d1cf, v30
	v_fmac_f32_e32 v31, 0x3f317217, v30
	v_cmp_lt_f32_e64 s[0:1], |v30|, s87
	s_nop 1
	v_cndmask_b32_e64 v30, v30, v31, s[0:1]
	v_cndmask_b32_e32 v31, 0, v231, vcc
	v_sub_f32_e32 v30, v30, v31
	ds_write_b32 v109, v30 offset:28
	global_load_dword v116, v[16:17], off offset:32
	v_rcp_f32_e32 v117, v29
	s_waitcnt vmcnt(0) lgkmcnt(0)
	v_sub_f32_e32 v30, 1.0, v116
	v_mul_f32_e32 v29, 1.0, v117
	v_rcp_f32_e32 v117, v28
	v_fmac_f32_e32 v116, v29, v30
	v_cmp_gt_f32_e32 vcc, s12, v116
	v_mul_f32_e32 v28, 1.0, v117
	s_nop 0
	v_cndmask_b32_e64 v29, 0, 32, vcc
	v_ldexp_f32 v29, v116, v29
	v_log_f32_e32 v29, v29
	s_nop 0
	v_mul_f32_e32 v30, 0x3f317217, v29
	v_fma_f32 v30, v29, s86, -v30
	v_fmac_f32_e32 v30, 0x3377d1cf, v29
	v_fmac_f32_e32 v30, 0x3f317217, v29
	v_cmp_lt_f32_e64 s[0:1], |v29|, s87
	s_nop 1
	v_cndmask_b32_e64 v29, v29, v30, s[0:1]
	v_cndmask_b32_e32 v30, 0, v231, vcc
	v_sub_f32_e32 v29, v29, v30
	ds_write_b32 v109, v29 offset:32
	global_load_dword v117, v[16:17], off offset:36
	s_waitcnt vmcnt(0) lgkmcnt(0)
	v_sub_f32_e32 v29, 1.0, v117
	v_fmac_f32_e32 v117, v28, v29
	v_cmp_gt_f32_e32 vcc, s12, v117
	s_nop 1
	v_cndmask_b32_e64 v28, 0, 32, vcc
	v_ldexp_f32 v28, v117, v28
	v_log_f32_e32 v28, v28
	s_nop 0
	v_mul_f32_e32 v29, 0x3f317217, v28
	v_fma_f32 v29, v28, s86, -v29
	v_fmac_f32_e32 v29, 0x3377d1cf, v28
	v_fmac_f32_e32 v29, 0x3f317217, v28
	v_cmp_lt_f32_e64 s[0:1], |v28|, s87
	s_nop 1
	v_cndmask_b32_e64 v28, v28, v29, s[0:1]
	v_cndmask_b32_e32 v29, 0, v231, vcc
	v_sub_f32_e32 v28, v28, v29
	ds_write_b32 v109, v28 offset:36
	global_load_dword v118, v[16:17], off offset:40
	v_rcp_f32_e32 v30, v27
	s_waitcnt vmcnt(0) lgkmcnt(0)
	v_sub_f32_e32 v28, 1.0, v118
	v_mul_f32_e32 v27, 1.0, v30
	v_rcp_f32_e32 v30, v26
	v_fmac_f32_e32 v118, v27, v28
	v_cmp_gt_f32_e32 vcc, s12, v118
	v_mul_f32_e32 v29, 1.0, v30
	s_nop 0
	v_cndmask_b32_e64 v26, 0, 32, vcc
	v_ldexp_f32 v26, v118, v26
	v_log_f32_e32 v26, v26
	s_nop 0
	v_mul_f32_e32 v27, 0x3f317217, v26
	v_fma_f32 v27, v26, s86, -v27
	v_fmac_f32_e32 v27, 0x3377d1cf, v26
	v_fmac_f32_e32 v27, 0x3f317217, v26
	v_cmp_lt_f32_e64 s[0:1], |v26|, s87
	s_nop 1
	v_cndmask_b32_e64 v26, v26, v27, s[0:1]
	v_cndmask_b32_e32 v27, 0, v231, vcc
	v_sub_f32_e32 v26, v26, v27
	ds_write_b32 v109, v26 offset:40
	global_load_dword v26, v[16:17], off offset:44
	s_waitcnt vmcnt(0) lgkmcnt(0)
	v_sub_f32_e32 v27, 1.0, v26
	v_fmac_f32_e32 v26, v29, v27
	v_cmp_gt_f32_e32 vcc, s12, v26
	s_nop 1
	v_cndmask_b32_e64 v27, 0, 32, vcc
	v_ldexp_f32 v27, v26, v27
	v_log_f32_e32 v27, v27
	s_nop 0
	v_mul_f32_e32 v28, 0x3f317217, v27
	v_fma_f32 v28, v27, s86, -v28
	v_fmac_f32_e32 v28, 0x3377d1cf, v27
	v_fmac_f32_e32 v28, 0x3f317217, v27
	v_cmp_lt_f32_e64 s[0:1], |v27|, s87
	s_nop 1
	v_cndmask_b32_e64 v27, v27, v28, s[0:1]
	v_cndmask_b32_e32 v28, 0, v231, vcc
	v_sub_f32_e32 v27, v27, v28
	ds_write_b32 v109, v27 offset:44
	global_load_dword v27, v[16:17], off offset:48
	v_rcp_f32_e32 v30, v25
	s_waitcnt vmcnt(0) lgkmcnt(0)
	v_sub_f32_e32 v28, 1.0, v27
	v_mul_f32_e32 v25, 1.0, v30
	v_rcp_f32_e32 v30, v24
	v_fmac_f32_e32 v27, v25, v28
	v_cmp_gt_f32_e32 vcc, s12, v27
	v_mul_f32_e32 v29, 1.0, v30
	s_nop 0
	v_cndmask_b32_e64 v24, 0, 32, vcc
	v_ldexp_f32 v24, v27, v24
	v_log_f32_e32 v24, v24
	s_nop 0
	v_mul_f32_e32 v25, 0x3f317217, v24
	v_fma_f32 v25, v24, s86, -v25
	v_fmac_f32_e32 v25, 0x3377d1cf, v24
	v_fmac_f32_e32 v25, 0x3f317217, v24
	v_cmp_lt_f32_e64 s[0:1], |v24|, s87
	s_nop 1
	v_cndmask_b32_e64 v24, v24, v25, s[0:1]
	v_cndmask_b32_e32 v25, 0, v231, vcc
	v_sub_f32_e32 v24, v24, v25
	ds_write_b32 v109, v24 offset:48
	global_load_dword v24, v[16:17], off offset:52
	s_waitcnt vmcnt(0) lgkmcnt(0)
	v_sub_f32_e32 v25, 1.0, v24
	v_fmac_f32_e32 v24, v29, v25
	v_cmp_gt_f32_e32 vcc, s12, v24
	s_nop 1
	v_cndmask_b32_e64 v25, 0, 32, vcc
	v_ldexp_f32 v25, v24, v25
	v_log_f32_e32 v25, v25
	s_nop 0
	v_mul_f32_e32 v28, 0x3f317217, v25
	v_fma_f32 v28, v25, s86, -v28
	v_fmac_f32_e32 v28, 0x3377d1cf, v25
	v_fmac_f32_e32 v28, 0x3f317217, v25
	v_cmp_lt_f32_e64 s[0:1], |v25|, s87
	s_nop 1
	v_cndmask_b32_e64 v25, v25, v28, s[0:1]
	v_cndmask_b32_e32 v28, 0, v231, vcc
	v_sub_f32_e32 v25, v25, v28
	ds_write_b32 v109, v25 offset:52
	global_load_dword v25, v[16:17], off offset:56
	v_rcp_f32_e32 v30, v23
	s_waitcnt vmcnt(0) lgkmcnt(0)
	v_sub_f32_e32 v28, 1.0, v25
	v_mul_f32_e32 v23, 1.0, v30
	v_rcp_f32_e32 v30, v22
	v_fmac_f32_e32 v25, v23, v28
	v_cmp_gt_f32_e32 vcc, s12, v25
	v_mul_f32_e32 v22, 1.0, v30
	s_nop 0
	v_cndmask_b32_e64 v23, 0, 32, vcc
	v_ldexp_f32 v23, v25, v23
	v_log_f32_e32 v23, v23
	s_nop 0
	v_mul_f32_e32 v28, 0x3f317217, v23
	v_fma_f32 v28, v23, s86, -v28
	v_fmac_f32_e32 v28, 0x3377d1cf, v23
	v_fmac_f32_e32 v28, 0x3f317217, v23
	v_cmp_lt_f32_e64 s[0:1], |v23|, s87
	s_nop 1
	v_cndmask_b32_e64 v23, v23, v28, s[0:1]
	v_cndmask_b32_e32 v28, 0, v231, vcc
	v_sub_f32_e32 v23, v23, v28
	ds_write_b32 v109, v23 offset:56
	global_load_dword v16, v[16:17], off offset:60
	s_waitcnt vmcnt(0) lgkmcnt(0)
	v_sub_f32_e32 v17, 1.0, v16
	v_fmac_f32_e32 v16, v22, v17
	v_cmp_gt_f32_e32 vcc, s12, v16
	s_nop 1
	v_cndmask_b32_e64 v17, 0, 32, vcc
	v_ldexp_f32 v17, v16, v17
	v_log_f32_e32 v17, v17
	s_nop 0
	v_mul_f32_e32 v22, 0x3f317217, v17
	v_fma_f32 v22, v17, s86, -v22
	v_fmac_f32_e32 v22, 0x3377d1cf, v17
	v_fmac_f32_e32 v22, 0x3f317217, v17
	v_cmp_lt_f32_e64 s[0:1], |v17|, s87
	s_nop 1
	v_cndmask_b32_e64 v17, v17, v22, s[0:1]
	v_cndmask_b32_e32 v22, 0, v231, vcc
	v_sub_f32_e32 v17, v17, v22
	ds_write_b32 v109, v17 offset:60
	v_ashrrev_i32_e32 v17, 7, v113
	v_and_b32_e32 v22, 0x7f, v113
	v_lshlrev_b32_e32 v23, 13, v17
	v_lshlrev_b32_e32 v28, 2, v22
	v_add3_u32 v113, 0, v28, v23
	s_mov_b64 s[0:1], -1
	s_and_b64 vcc, exec, s[18:19]
	s_waitcnt lgkmcnt(0)
	s_barrier
	s_cbranch_vccz .LBB0_739
	ds_read2st64_b32 v[164:165], v113 offset0:28 offset1:30
	ds_read2st64_b32 v[166:167], v113 offset0:24 offset1:26
	ds_read2st64_b32 v[168:169], v113 offset0:20 offset1:22
	ds_read2st64_b32 v[170:171], v113 offset0:16 offset1:18
	ds_read2st64_b32 v[172:173], v113 offset0:12 offset1:14
	ds_read2st64_b32 v[174:175], v113 offset0:8 offset1:10
	ds_read2st64_b32 v[176:177], v113 offset0:4 offset1:6
	ds_read2st64_b32 v[178:179], v113 offset1:2
	s_mov_b64 s[0:1], 0
	s_waitcnt lgkmcnt(0)
	v_add_f32_e32 v29, 0, v165
	v_add_f32_e32 v119, v29, v164
	ds_write2st64_b32 v113, v119, v29 offset0:28 offset1:30
	v_add_f32_e32 v29, v119, v167
	v_add_f32_e32 v119, v29, v166
	ds_write2st64_b32 v113, v119, v29 offset0:24 offset1:26
	v_add_f32_e32 v29, v119, v169
	v_add_f32_e32 v119, v29, v168
	ds_write2st64_b32 v113, v119, v29 offset0:20 offset1:22
	v_add_f32_e32 v29, v119, v171
	v_add_f32_e32 v119, v29, v170
	ds_write2st64_b32 v113, v119, v29 offset0:16 offset1:18
	v_add_f32_e32 v29, v119, v173
	v_add_f32_e32 v119, v29, v172
	ds_write2st64_b32 v113, v119, v29 offset0:12 offset1:14
	v_add_f32_e32 v29, v119, v175
	v_add_f32_e32 v119, v29, v174
	ds_write2st64_b32 v113, v119, v29 offset0:8 offset1:10
	v_add_f32_e32 v29, v119, v177
	v_add_f32_e32 v119, v29, v176
	ds_write2st64_b32 v113, v119, v29 offset0:4 offset1:6
	v_add_f32_e32 v29, v119, v179
	v_add_f32_e32 v30, v29, v178
	ds_write2st64_b32 v113, v30, v29 offset1:2
.LBB0_739:
	s_andn2_b64 vcc, exec, s[0:1]
	s_cbranch_vccnz .LBB0_741
	ds_read2st64_b32 v[164:165], v113 offset1:2
	ds_read2st64_b32 v[166:167], v113 offset0:4 offset1:6
	ds_read2st64_b32 v[168:169], v113 offset0:8 offset1:10
	ds_read2st64_b32 v[170:171], v113 offset0:12 offset1:14
	ds_read2st64_b32 v[172:173], v113 offset0:16 offset1:18
	ds_read2st64_b32 v[174:175], v113 offset0:20 offset1:22
	ds_read2st64_b32 v[176:177], v113 offset0:24 offset1:26
	ds_read2st64_b32 v[178:179], v113 offset0:28 offset1:30
	s_waitcnt lgkmcnt(0)
	v_add_f32_e32 v29, 0, v164
	v_add_f32_e32 v119, v29, v165
	ds_write2st64_b32 v113, v29, v119 offset1:2
	v_add_f32_e32 v29, v119, v166
	v_add_f32_e32 v119, v29, v167
	ds_write2st64_b32 v113, v29, v119 offset0:4 offset1:6
	v_add_f32_e32 v29, v119, v168
	v_add_f32_e32 v119, v29, v169
	ds_write2st64_b32 v113, v29, v119 offset0:8 offset1:10
	v_add_f32_e32 v29, v119, v170
	v_add_f32_e32 v119, v29, v171
	ds_write2st64_b32 v113, v29, v119 offset0:12 offset1:14
	v_add_f32_e32 v29, v119, v172
	v_add_f32_e32 v119, v29, v173
	ds_write2st64_b32 v113, v29, v119 offset0:16 offset1:18
	v_add_f32_e32 v29, v119, v174
	v_add_f32_e32 v119, v29, v175
	ds_write2st64_b32 v113, v29, v119 offset0:20 offset1:22
	v_add_f32_e32 v29, v119, v176
	v_add_f32_e32 v119, v29, v177
	ds_write2st64_b32 v113, v29, v119 offset0:24 offset1:26
	v_add_f32_e32 v29, v119, v178
	v_add_f32_e32 v30, v29, v179
	ds_write2st64_b32 v113, v29, v30 offset0:28 offset1:30

.LBB0_753:
	v_sub_f32_e32 v23, 1.0, v115
	v_sub_f32_e32 v22, 1.0, v114
	s_barrier
	ds_read2st64_b32 v[164:165], v113 offset1:2
	ds_read2st64_b32 v[166:167], v113 offset0:4 offset1:6
	ds_read2st64_b32 v[168:169], v113 offset0:8 offset1:10
	ds_read2st64_b32 v[170:171], v113 offset0:12 offset1:14
	ds_read2st64_b32 v[172:173], v113 offset0:16 offset1:18
	ds_read2st64_b32 v[174:175], v113 offset0:20 offset1:22
	ds_read2st64_b32 v[176:177], v113 offset0:24 offset1:26
	ds_read2st64_b32 v[178:179], v113 offset0:28 offset1:30
	v_sub_f32_e32 v31, 1.0, v16
	v_sub_f32_e32 v17, 1.0, v112
	v_sub_f32_e32 v16, 1.0, v111
	v_sub_f32_e32 v30, 1.0, v25
	s_waitcnt lgkmcnt(0)
	v_add_f32_e32 v111, v119, v164
	v_add_f32_e32 v112, v119, v165
	ds_write2st64_b32 v113, v111, v112 offset1:2
	v_sub_f32_e32 v29, 1.0, v24
	v_sub_f32_e32 v28, 1.0, v27
	v_sub_f32_e32 v27, 1.0, v26
	v_add_f32_e32 v111, v119, v166
	v_add_f32_e32 v112, v119, v167
	ds_write2st64_b32 v113, v111, v112 offset0:4 offset1:6
	v_sub_f32_e32 v26, 1.0, v118
	v_sub_f32_e32 v25, 1.0, v117
	v_sub_f32_e32 v24, 1.0, v116
	v_add_f32_e32 v111, v119, v168
	v_add_f32_e32 v112, v119, v169
	ds_write2st64_b32 v113, v111, v112 offset0:8 offset1:10
	v_sub_f32_e32 v21, 1.0, v21
	v_sub_f32_e32 v20, 1.0, v20
	v_sub_f32_e32 v19, 1.0, v19
	v_add_f32_e32 v111, v119, v170
	v_add_f32_e32 v112, v119, v171
	ds_write2st64_b32 v113, v111, v112 offset0:12 offset1:14
	v_sub_f32_e32 v18, 1.0, v18
	s_mov_b64 s[0:1], 0
	v_add_f32_e32 v111, v119, v172
	v_add_f32_e32 v112, v119, v173
	ds_write2st64_b32 v113, v111, v112 offset0:16 offset1:18
	v_add_f32_e32 v111, v119, v174
	v_add_f32_e32 v112, v119, v175
	ds_write2st64_b32 v113, v111, v112 offset0:20 offset1:22
	v_add_f32_e32 v111, v119, v176
	v_add_f32_e32 v112, v119, v177
	ds_write2st64_b32 v113, v111, v112 offset0:24 offset1:26
	v_add_f32_e32 v111, v119, v178
	v_add_f32_e32 v112, v119, v179
	ds_write2st64_b32 v113, v111, v112 offset0:28 offset1:30
	s_waitcnt lgkmcnt(0)
	s_barrier

.LBB0_1906:
	v_mul_u32_u24_e32 v200, 0x90, v211
	v_add3_u32 v218, s3, v200, v130
	v_add_u32_e32 v247, 0x3000, v218
	v_add_u32_e32 v248, 0x4000, v218
	ds_read2_b64 v[200:203], v247 offset0:128 offset1:130
	ds_read2_b64 v[224:227], v248 offset0:192 offset1:194
	v_sub_f32_e32 v99, v99, v238
	v_exp_f32_e32 v246, v99
	v_sub_f32_e32 v99, v100, v238
	v_exp_f32_e32 v100, v99
	v_sub_f32_e32 v99, v101, v238
	v_pk_add_f32 v[112:113], v[112:113], v[238:239] op_sel:[0,1] op_sel_hi:[1,1] neg_lo:[0,1] neg_hi:[0,1]
	v_pk_add_f32 v[114:115], v[114:115], v[238:239] op_sel:[0,1] op_sel_hi:[1,1] neg_lo:[0,1] neg_hi:[0,1]
	v_pk_add_f32 v[116:117], v[116:117], v[238:239] op_sel:[0,1] op_sel_hi:[1,1] neg_lo:[0,1] neg_hi:[0,1]
	v_pk_add_f32 v[118:119], v[118:119], v[238:239] op_sel:[0,1] op_sel_hi:[1,1] neg_lo:[0,1] neg_hi:[0,1]
	v_exp_f32_e32 v101, v99
	v_sub_f32_e32 v99, v102, v238
	v_exp_f32_e32 v112, v112
	v_exp_f32_e32 v113, v113
	v_exp_f32_e32 v114, v114
	v_exp_f32_e32 v115, v115
	v_exp_f32_e32 v116, v116
	v_exp_f32_e32 v117, v117
	v_exp_f32_e32 v118, v118
	v_exp_f32_e32 v119, v119
	v_pk_add_f32 v[96:97], v[96:97], v[238:239] op_sel_hi:[1,0] neg_lo:[0,1] neg_hi:[0,1]
	v_sub_f32_e32 v98, v98, v238
	v_exp_f32_e32 v102, v99
	v_sub_f32_e32 v99, v103, v238
	v_exp_f32_e32 v96, v96
	v_exp_f32_e32 v97, v97
	v_exp_f32_e32 v98, v98
	v_exp_f32_e32 v103, v99
	v_cvt_pk_bf16_f32 v194, v112, v113
	v_cvt_pk_bf16_f32 v195, v114, v115
	v_cvt_pk_bf16_f32 v196, v116, v117
	v_cvt_pk_bf16_f32 v197, v118, v119
	ds_read2_b64 v[218:221], v247 offset0:132 offset1:134
	v_sub_f32_e32 v120, v120, v239
	s_waitcnt lgkmcnt(0)
	v_mfma_f32_32x32x16_bf16 v[32:47], v[200:203], v[194:197], v[32:47]
	v_sub_f32_e32 v121, v121, v239
	v_pk_add_f32 v[122:123], v[122:123], v[238:239] op_sel:[0,1] op_sel_hi:[1,1] neg_lo:[0,1] neg_hi:[0,1]
	v_pk_add_f32 v[124:125], v[124:125], v[238:239] op_sel:[0,1] op_sel_hi:[1,1] neg_lo:[0,1] neg_hi:[0,1]
	v_sub_f32_e32 v126, v126, v239
	v_sub_f32_e32 v99, v127, v239
	v_mfma_f32_32x32x16_bf16 v[48:63], v[224:227], v[194:197], v[48:63]
	v_cvt_pk_bf16_f32 v194, v96, v97
	v_cvt_pk_bf16_f32 v195, v98, v246
	v_cvt_pk_bf16_f32 v196, v100, v101
	v_cvt_pk_bf16_f32 v197, v102, v103
	v_exp_f32_e32 v120, v120
	v_exp_f32_e32 v121, v121
	v_exp_f32_e32 v122, v122
	v_mfma_f32_32x32x16_bf16 v[16:31], v[200:203], v[194:197], v[16:31]
	v_exp_f32_e32 v123, v123
	v_exp_f32_e32 v124, v124
	v_exp_f32_e32 v125, v125
	v_exp_f32_e32 v126, v126
	v_exp_f32_e32 v99, v99
	v_pk_add_f32 v[104:105], v[104:105], v[238:239] op_sel_hi:[1,0] neg_lo:[0,1] neg_hi:[0,1]
	v_mfma_f32_32x32x16_bf16 v[0:15], v[224:227], v[194:197], v[0:15]
	ds_read2_b64 v[194:197], v248 offset0:196 offset1:198
	v_pk_add_f32 v[106:107], v[106:107], v[238:239] op_sel_hi:[1,0] neg_lo:[0,1] neg_hi:[0,1]
	v_pk_add_f32 v[108:109], v[108:109], v[238:239] op_sel_hi:[1,0] neg_lo:[0,1] neg_hi:[0,1]
	v_pk_add_f32 v[110:111], v[110:111], v[238:239] op_sel_hi:[1,0] neg_lo:[0,1] neg_hi:[0,1]
	v_exp_f32_e32 v104, v104
	v_exp_f32_e32 v105, v105
	v_exp_f32_e32 v106, v106
	v_exp_f32_e32 v107, v107
	v_exp_f32_e32 v108, v108
	v_exp_f32_e32 v109, v109
	v_exp_f32_e32 v110, v110
	v_exp_f32_e32 v111, v111
	v_cvt_pk_bf16_f32 v200, v120, v121
	v_cvt_pk_bf16_f32 v201, v122, v123
	v_cvt_pk_bf16_f32 v202, v124, v125
	v_cvt_pk_bf16_f32 v203, v126, v99
	ds_read2_b64 v[224:227], v247 offset0:136 offset1:138
	v_sub_f32_e32 v64, v64, v239
	v_mfma_f32_32x32x16_bf16 v[32:47], v[218:221], v[200:203], v[32:47]
	v_sub_f32_e32 v65, v65, v239
	v_pk_add_f32 v[66:67], v[66:67], v[238:239] op_sel:[0,1] op_sel_hi:[1,1] neg_lo:[0,1] neg_hi:[0,1]
	v_pk_add_f32 v[68:69], v[68:69], v[238:239] op_sel:[0,1] op_sel_hi:[1,1] neg_lo:[0,1] neg_hi:[0,1]
	v_pk_add_f32 v[70:71], v[70:71], v[238:239] op_sel:[0,1] op_sel_hi:[1,1] neg_lo:[0,1] neg_hi:[0,1]
	s_waitcnt lgkmcnt(0)
	v_mfma_f32_32x32x16_bf16 v[48:63], v[194:197], v[200:203], v[48:63]
	v_cvt_pk_bf16_f32 v200, v104, v105
	v_cvt_pk_bf16_f32 v201, v106, v107
	v_cvt_pk_bf16_f32 v202, v108, v109
	v_cvt_pk_bf16_f32 v203, v110, v111
	v_pk_add_f32 v[80:81], v[80:81], v[238:239] op_sel_hi:[1,0] neg_lo:[0,1] neg_hi:[0,1]
	v_sub_f32_e32 v82, v82, v238
	v_mfma_f32_32x32x16_bf16 v[0:15], v[194:197], v[200:203], v[0:15]
	ds_read2_b64 v[194:197], v248 offset0:200 offset1:202
	v_sub_f32_e32 v83, v83, v238
	v_pk_add_f32 v[84:85], v[84:85], v[238:239] op_sel_hi:[1,0] neg_lo:[0,1] neg_hi:[0,1]
	v_pk_add_f32 v[86:87], v[86:87], v[238:239] op_sel_hi:[1,0] neg_lo:[0,1] neg_hi:[0,1]
	v_exp_f32_e32 v64, v64
	v_mfma_f32_32x32x16_bf16 v[16:31], v[218:221], v[200:203], v[16:31]
	v_exp_f32_e32 v65, v65
	v_exp_f32_e32 v66, v66
	v_exp_f32_e32 v67, v67
	v_exp_f32_e32 v68, v68
	v_exp_f32_e32 v69, v69
	v_exp_f32_e32 v70, v70
	v_exp_f32_e32 v71, v71
	v_exp_f32_e32 v80, v80
	v_exp_f32_e32 v81, v81
	v_exp_f32_e32 v82, v82
	v_exp_f32_e32 v83, v83
	v_exp_f32_e32 v84, v84
	v_exp_f32_e32 v85, v85
	v_exp_f32_e32 v86, v86
	v_exp_f32_e32 v87, v87
	v_cvt_pk_bf16_f32 v218, v64, v65
	v_cvt_pk_bf16_f32 v219, v66, v67
	v_cvt_pk_bf16_f32 v220, v68, v69
	v_cvt_pk_bf16_f32 v221, v70, v71
	v_cvt_pk_bf16_f32 v200, v80, v81
	v_cvt_pk_bf16_f32 v201, v82, v83
	v_cvt_pk_bf16_f32 v202, v84, v85
	v_cvt_pk_bf16_f32 v203, v86, v87
	v_mfma_f32_32x32x16_bf16 v[32:47], v[224:227], v[218:221], v[32:47]
	v_pk_add_f32 v[72:73], v[72:73], v[238:239] op_sel:[0,1] op_sel_hi:[1,1] neg_lo:[0,1] neg_hi:[0,1]
	v_pk_add_f32 v[74:75], v[74:75], v[238:239] op_sel:[0,1] op_sel_hi:[1,1] neg_lo:[0,1] neg_hi:[0,1]
	v_pk_add_f32 v[76:77], v[76:77], v[238:239] op_sel:[0,1] op_sel_hi:[1,1] neg_lo:[0,1] neg_hi:[0,1]
	v_sub_f32_e32 v78, v78, v239
	s_waitcnt lgkmcnt(0)
	v_mfma_f32_32x32x16_bf16 v[48:63], v[194:197], v[218:221], v[48:63]
	v_sub_f32_e32 v79, v79, v239
	v_pk_add_f32 v[88:89], v[88:89], v[238:239] op_sel_hi:[1,0] neg_lo:[0,1] neg_hi:[0,1]
	v_pk_add_f32 v[90:91], v[90:91], v[238:239] op_sel_hi:[1,0] neg_lo:[0,1] neg_hi:[0,1]
	v_pk_add_f32 v[92:93], v[92:93], v[238:239] op_sel_hi:[1,0] neg_lo:[0,1] neg_hi:[0,1]
	v_mfma_f32_32x32x16_bf16 v[16:31], v[224:227], v[200:203], v[16:31]
	ds_read2_b64 v[224:227], v247 offset0:140 offset1:142
	v_pk_add_f32 v[94:95], v[94:95], v[238:239] op_sel_hi:[1,0] neg_lo:[0,1] neg_hi:[0,1]
	v_exp_f32_e32 v72, v72
	v_exp_f32_e32 v73, v73
	v_exp_f32_e32 v74, v74
	v_exp_f32_e32 v75, v75
	v_mfma_f32_32x32x16_bf16 v[0:15], v[194:197], v[200:203], v[0:15]
	ds_read2_b64 v[194:197], v248 offset0:204 offset1:206
	v_exp_f32_e32 v76, v76
	v_exp_f32_e32 v77, v77
	v_exp_f32_e32 v78, v78
	v_exp_f32_e32 v79, v79
	v_exp_f32_e32 v88, v88
	v_exp_f32_e32 v89, v89
	v_exp_f32_e32 v90, v90
	v_exp_f32_e32 v91, v91
	v_exp_f32_e32 v92, v92
	v_exp_f32_e32 v93, v93
	v_exp_f32_e32 v94, v94
	v_exp_f32_e32 v95, v95
	v_cvt_pk_bf16_f32 v218, v72, v73
	v_cvt_pk_bf16_f32 v219, v74, v75
	v_cvt_pk_bf16_f32 v220, v76, v77
	v_cvt_pk_bf16_f32 v221, v78, v79
	v_cvt_pk_bf16_f32 v200, v88, v89
	v_cvt_pk_bf16_f32 v201, v90, v91
	v_cvt_pk_bf16_f32 v202, v92, v93
	v_cvt_pk_bf16_f32 v203, v94, v95
	s_waitcnt lgkmcnt(0)
	v_mfma_f32_32x32x16_bf16 v[32:47], v[224:227], v[218:221], v[32:47]
	s_cmp_eq_u32 s2, 1
	s_cselect_b32 s2, 0x5800, 0
	s_add_i32 s9, s2, 0
	v_add3_u32 v127, s9, v240, v241
	s_waitcnt vmcnt(0)
	ds_write_b128 v127, v[184:187]
	v_mfma_f32_32x32x16_bf16 v[48:63], v[194:197], v[218:221], v[48:63]
	v_mfma_f32_32x32x16_bf16 v[16:31], v[224:227], v[200:203], v[16:31]
	v_mfma_f32_32x32x16_bf16 v[0:15], v[194:197], v[200:203], v[0:15]
	s_and_saveexec_b64 s[2:3], s[42:43]
	s_cbranch_execz .LBB0_1899
	v_add3_u32 v127, s9, v243, v242
	ds_write_b128 v127, v[180:183]
	s_branch .LBB0_1899
